# skip XCD-leader L2 write-back at the two full seams whose consumers read only same-XCD clique data
# baseline (speedup 1.0000x reference)
; __device__ __forceinline__ unsigned xb_add(unsigned* p, unsigned v) { return __hip_atomic_fetch_add(p, v, __ATOMIC_RELAXED, __HIP_MEMORY_SCOPE_AGENT); }
; __device__ __forceinline__ void xcd_barrier(const XcdBarrier& b) {
;     ...
;         const unsigned old = xb_add(&bar[XB_XSUB(b.x)], 1u);
;         const unsigned gen = old / nloc;
;         if (old + 1u == (gen + 1u) * nloc) {
;             __builtin_amdgcn_fence(__ATOMIC_RELEASE, "agent");
;             asm volatile("s_waitcnt vmcnt(0)" ::: "memory");
;             const unsigned og = xb_add(&bar[XB_TOP], 1u);
;             const unsigned tg = og / nx;
;             if (og + 1u == (tg + 1u) * nx) xb_add(&bar[XB_TOPGEN], 1u);
.LBB0_662:
	s_andn2_saveexec_b64 s[12:13], s[12:13]
	s_cbranch_execz .LBB0_682
	s_mov_b64 s[14:15], exec
	v_readlane_b32 s16, v255, 40
	s_nop 1
	s_cmp_lg_u32 s16, 0
	s_cbranch_scc1 .Lnw1
	buffer_wbl2 sc1
.Lnw1:
	s_waitcnt lgkmcnt(0)
	s_waitcnt vmcnt(0)
	v_mbcnt_lo_u32_b32 v0, s14, 0
	v_mbcnt_hi_u32_b32 v0, s15, v0
	v_cmp_eq_u32_e32 vcc, 0, v0
	s_and_saveexec_b64 s[16:17], vcc
	s_cbranch_execz .LBB0_665
	s_bcnt1_i32_b64 s2, s[14:15]
	v_mov_b32_e32 v3, s2
	v_mov_b32_e32 v4, 0x4000
	global_atomic_add v3, v4, v3, s[8:9] offset:1024 sc0

; __device__ __forceinline__ unsigned xb_ld(unsigned* p)              { return __hip_atomic_load(p, __ATOMIC_RELAXED, __HIP_MEMORY_SCOPE_AGENT); }
; __device__ __forceinline__ unsigned xb_add(unsigned* p, unsigned v) { return __hip_atomic_fetch_add(p, v, __ATOMIC_RELAXED, __HIP_MEMORY_SCOPE_AGENT); }
; #define XB_SPIN(cond, bar) do { unsigned _sp = 0; while (cond) { __builtin_amdgcn_s_sleep(1); \
;     if ((++_sp & 255u) == 0u) { if (xb_ld(&(bar)[XB_TMO])) break; if (_sp > XB_SPIN_CAP) { atomicAdd(&(bar)[XB_TMO], 1u); break; } } } } while (0)
; __device__ __forceinline__ void xcd_barrier(const XcdBarrier& b) {
;     ...
;         if (old + 1u == (gen + 1u) * nloc) {
;             __builtin_amdgcn_fence(__ATOMIC_RELEASE, "agent");
;             asm volatile("s_waitcnt vmcnt(0)" ::: "memory");
;             const unsigned og = xb_add(&bar[XB_TOP], 1u);
;             const unsigned tg = og / nx;
;             if (og + 1u == (tg + 1u) * nx) xb_add(&bar[XB_TOPGEN], 1u);
;             else XB_SPIN(xb_ld(&bar[XB_TOPGEN]) == tg, bar);
;             __builtin_amdgcn_fence(__ATOMIC_ACQUIRE, "agent");
;             xb_add(&bar[XB_XGEN(b.x)], 1u);
.Lnw4:
	s_waitcnt lgkmcnt(0)
	s_waitcnt vmcnt(0)
	v_mbcnt_lo_u32_b32 v2, s14, 0
	v_mbcnt_hi_u32_b32 v2, s15, v2
	v_cmp_eq_u32_e32 vcc, 0, v2
	s_and_saveexec_b64 s[16:17], vcc
	s_cbranch_execz .LBB0_1950
	s_bcnt1_i32_b64 s2, s[14:15]
	v_mov_b32_e32 v3, s2
	v_mov_b32_e32 v4, 0x4000
	global_atomic_add v3, v4, v3, s[8:9] offset:1024 sc0
